# strategy 4: one static s_setprio 1 for waves 4-7 before the GEMM unit loops, all per-segment setprio flips deleted (SwiGLU+Resid K-loops)
# speedup vs baseline: 1.0163x; 1.0163x over previous
.LBB0_483:
	s_and_b64 s[38:39], s[12:13], exec
	s_cselect_b32 s38, 2, 3
	s_and_b64 s[6:7], s[6:7], exec
	s_mul_i32 s40, s75, 3
	s_cselect_b32 s6, 1, s38
	s_add_i32 s6, s6, s40
	s_lshl_b32 s6, s6, 17
	s_add_u32 s6, s26, s6
	s_addc_u32 s7, s27, 0
	s_waitcnt vmcnt(8)
	s_barrier
	v_bfe_u32 v199, v12, 4, 2
	v_and_b32_e32 v200, 15, v12
	v_lshlrev_b32_e32 v0, 4, v199
	v_lshlrev_b32_e32 v1, 2, v12
	v_cndmask_b32_e64 v174, 0.5, 1.0, s[12:13]
	v_lshl_or_b32 v0, v200, 6, v0
	s_lshl_b32 s12, s25, 13
	v_and_b32_e32 v1, 32, v1
	v_bitop3_b32 v2, v0, s12, v1 bitop3:0xde
	s_lshl_b32 s12, s24, 5
	s_and_b32 s79, s12, 0x60
	s_lshl_b32 s12, s79, 7
	v_bitop3_b32 v201, v0, s12, v1 bitop3:0xde
	v_add_u32_e32 v0, v18, v16
	s_lshr_b32 s64, s17, 6
	v_add_lshl_u32 v0, v0, v17, 1
	v_mov_b32_e32 v1, v159
	s_lshl_b32 s65, s25, 6
	s_waitcnt vmcnt(6)
	s_add_i32 s80, s64, -2
	v_lshl_add_u64 v[176:177], s[8:9], 0, v[0:1]
	v_add_u32_e32 v0, v15, v13
	s_cmpk_lt_u32 s16, 0x100
	v_add_lshl_u32 v0, v0, v14, 1
	v_readlane_b32 s16, v242, 58
	s_cselect_b64 s[12:13], -1, 0
	v_mov_b32_e32 v175, v174
	v_lshl_add_u64 v[178:179], s[8:9], 0, v[0:1]
	s_mov_b32 s81, 0
	v_add_u32_e32 v202, 0, v2
	v_readlane_b32 s84, v242, 57
	s_mov_b32 s85, s16
	s_barrier
	v_readlane_b32 s17, v242, 59
	s_and_b64 vcc, exec, s[12:13]
	s_cbranch_vccnz .Lprio_rs_done
	s_setprio 1

.LBB0_496:
	s_add_u32 s2, s2, 0x80
	s_addc_u32 s3, s3, 0
	s_add_u32 s40, s34, 0x100
	s_addc_u32 s41, s35, 0
	s_mov_b32 s34, 0
	s_waitcnt lgkmcnt(0)
	s_waitcnt vmcnt(0)
	s_add_i32 s86, s34, 2
	s_add_u32 s62, s2, 0x80
	s_addc_u32 s35, s3, 0
	s_add_i32 s63, 0, 0x10000
	s_cmp_eq_u32 s80, s34
	s_cselect_b32 s35, s17, s35
	s_cselect_b32 s34, s16, s62
	s_cselect_b32 s89, s25, s41
	s_cselect_b32 s88, s24, s40
	s_add_i32 s62, 0, 0x14000
	v_add_u32_e32 v140, s63, v201
	v_add_u32_e32 v180, s62, v201
	ds_read_b128 v[128:131], v140
	ds_read_b128 v[132:135], v140 offset:1024
	ds_read_b128 v[136:139], v140 offset:2048
	ds_read_b128 v[140:143], v140 offset:3072
	ds_read_b128 v[144:147], v180
	ds_read_b128 v[148:151], v180 offset:1024
	ds_read_b128 v[152:155], v180 offset:2048
	ds_read_b128 v[180:183], v180 offset:3072
	v_lshl_add_u64 v[192:193], s[2:3], 0, v[176:177]
	s_add_i32 m0, s48, 0xc000
	ds_read_b128 v[184:187], v202
	ds_read_b128 v[188:191], v202 offset:1024
	ds_read_b128 v[204:207], v202 offset:2048
	ds_read_b128 v[208:211], v202 offset:3072
	ds_read_b128 v[212:215], v202 offset:4096
	ds_read_b128 v[216:219], v202 offset:5120
	ds_read_b128 v[220:223], v202 offset:6144
	ds_read_b128 v[224:227], v202 offset:7168
	global_load_lds_dwordx4 v[192:193], off
	v_lshl_add_u64 v[192:193], s[2:3], 0, v[178:179]
	s_add_i32 m0, s48, 0xe000
	s_nop 0
	global_load_lds_dwordx4 v[192:193], off
	s_waitcnt vmcnt(8)
	s_waitcnt lgkmcnt(0)
	s_barrier
	v_mfma_f32_16x16x32_bf16 v[124:127], v[128:131], v[184:187], 0
	v_mfma_f32_16x16x32_bf16 v[120:123], v[136:139], v[184:187], 0
	v_mfma_f32_16x16x32_bf16 v[108:111], v[128:131], v[204:207], 0
	v_mfma_f32_16x16x32_bf16 v[104:107], v[136:139], v[204:207], 0
	v_mfma_f32_16x16x32_bf16 v[92:95], v[128:131], v[212:215], 0
	v_mfma_f32_16x16x32_bf16 v[88:91], v[136:139], v[212:215], 0
	v_mfma_f32_16x16x32_bf16 v[76:79], v[128:131], v[220:223], 0
	v_mfma_f32_16x16x32_bf16 v[72:75], v[136:139], v[220:223], 0
	v_mfma_f32_16x16x32_bf16 v[124:127], v[132:135], v[188:191], v[124:127]
	v_mfma_f32_16x16x32_bf16 v[120:123], v[140:143], v[188:191], v[120:123]
	v_mfma_f32_16x16x32_bf16 v[108:111], v[132:135], v[208:211], v[108:111]
	v_mfma_f32_16x16x32_bf16 v[104:107], v[140:143], v[208:211], v[104:107]
	v_mfma_f32_16x16x32_bf16 v[92:95], v[132:135], v[216:219], v[92:95]
	v_mfma_f32_16x16x32_bf16 v[88:91], v[140:143], v[216:219], v[88:91]
	v_mfma_f32_16x16x32_bf16 v[76:79], v[132:135], v[224:227], v[76:79]
	v_mfma_f32_16x16x32_bf16 v[72:75], v[140:143], v[224:227], v[72:75]
	v_mfma_f32_16x16x32_bf16 v[116:119], v[144:147], v[184:187], 0
	v_mfma_f32_16x16x32_bf16 v[112:115], v[152:155], v[184:187], 0
	v_mfma_f32_16x16x32_bf16 v[100:103], v[144:147], v[204:207], 0
	v_mfma_f32_16x16x32_bf16 v[96:99], v[152:155], v[204:207], 0
	v_mfma_f32_16x16x32_bf16 v[84:87], v[144:147], v[212:215], 0
	v_mfma_f32_16x16x32_bf16 v[80:83], v[152:155], v[212:215], 0
	v_mfma_f32_16x16x32_bf16 v[68:71], v[144:147], v[220:223], 0
	v_mfma_f32_16x16x32_bf16 v[64:67], v[152:155], v[220:223], 0
	v_mfma_f32_16x16x32_bf16 v[116:119], v[148:151], v[188:191], v[116:119]
	v_mfma_f32_16x16x32_bf16 v[112:115], v[180:183], v[188:191], v[112:115]
	v_mfma_f32_16x16x32_bf16 v[100:103], v[148:151], v[208:211], v[100:103]
	v_mfma_f32_16x16x32_bf16 v[96:99], v[180:183], v[208:211], v[96:99]
	v_mfma_f32_16x16x32_bf16 v[84:87], v[148:151], v[216:219], v[84:87]
	v_mfma_f32_16x16x32_bf16 v[80:83], v[180:183], v[216:219], v[80:83]
	v_mfma_f32_16x16x32_bf16 v[68:71], v[148:151], v[224:227], v[68:71]
	v_mfma_f32_16x16x32_bf16 v[64:67], v[180:183], v[224:227], v[64:67]
	s_barrier
	s_add_i32 s63, s63, s47
	v_lshl_add_u64 v[192:193], s[88:89], 0, v[158:159]
	s_mov_b32 m0, s63
	ds_read_b128 v[184:187], v202 offset:16384
	ds_read_b128 v[188:191], v202 offset:17408
	ds_read_b128 v[204:207], v202 offset:18432
	ds_read_b128 v[208:211], v202 offset:19456
	ds_read_b128 v[212:215], v202 offset:20480
	ds_read_b128 v[216:219], v202 offset:21504
	ds_read_b128 v[220:223], v202 offset:22528
	ds_read_b128 v[224:227], v202 offset:23552
	global_load_lds_dwordx4 v[192:193], off
	s_add_i32 m0, s63, 0x2000
	v_lshl_add_u64 v[228:229], s[88:89], 0, v[168:169]
	s_add_u32 s88, s88, s8
	s_addc_u32 s89, s89, 0
	s_add_i32 s62, s62, s47
	global_load_lds_dwordx4 v[228:229], off
	v_lshl_add_u64 v[230:231], s[88:89], 0, v[158:159]
	s_mov_b32 m0, s62
	v_lshl_add_u64 v[232:233], s[88:89], 0, v[168:169]
	global_load_lds_dwordx4 v[230:231], off
	s_add_i32 m0, s62, 0x2000
	v_lshl_add_u64 v[234:235], s[34:35], 0, v[172:173]
	global_load_lds_dwordx4 v[232:233], off
	s_mov_b32 m0, s48
	v_lshl_add_u64 v[236:237], s[34:35], 0, v[170:171]
	global_load_lds_dwordx4 v[234:235], off
	s_mov_b32 m0, s49
	s_nop 0
	global_load_lds_dwordx4 v[236:237], off
	s_waitcnt vmcnt(8)
	s_waitcnt lgkmcnt(0)
	s_barrier
	v_mfma_f32_16x16x32_bf16 v[60:63], v[128:131], v[184:187], 0
	v_mfma_f32_16x16x32_bf16 v[56:59], v[136:139], v[184:187], 0
	v_mfma_f32_16x16x32_bf16 v[44:47], v[128:131], v[204:207], 0
	v_mfma_f32_16x16x32_bf16 v[40:43], v[136:139], v[204:207], 0
	v_mfma_f32_16x16x32_bf16 v[28:31], v[128:131], v[212:215], 0
	v_mfma_f32_16x16x32_bf16 v[24:27], v[136:139], v[212:215], 0
	v_mfma_f32_16x16x32_bf16 v[12:15], v[128:131], v[220:223], 0
	v_mfma_f32_16x16x32_bf16 v[8:11], v[136:139], v[220:223], 0
	v_mfma_f32_16x16x32_bf16 v[60:63], v[132:135], v[188:191], v[60:63]
	v_mfma_f32_16x16x32_bf16 v[56:59], v[140:143], v[188:191], v[56:59]
	v_mfma_f32_16x16x32_bf16 v[44:47], v[132:135], v[208:211], v[44:47]
	v_mfma_f32_16x16x32_bf16 v[40:43], v[140:143], v[208:211], v[40:43]
	v_mfma_f32_16x16x32_bf16 v[28:31], v[132:135], v[216:219], v[28:31]
	v_mfma_f32_16x16x32_bf16 v[24:27], v[140:143], v[216:219], v[24:27]
	v_mfma_f32_16x16x32_bf16 v[12:15], v[132:135], v[224:227], v[12:15]
	v_mfma_f32_16x16x32_bf16 v[8:11], v[140:143], v[224:227], v[8:11]
	v_mfma_f32_16x16x32_bf16 v[52:55], v[144:147], v[184:187], 0
	v_mfma_f32_16x16x32_bf16 v[48:51], v[152:155], v[184:187], 0
	v_mfma_f32_16x16x32_bf16 v[36:39], v[144:147], v[204:207], 0
	v_mfma_f32_16x16x32_bf16 v[32:35], v[152:155], v[204:207], 0
	v_mfma_f32_16x16x32_bf16 v[20:23], v[144:147], v[212:215], 0
	v_mfma_f32_16x16x32_bf16 v[16:19], v[152:155], v[212:215], 0
	v_mfma_f32_16x16x32_bf16 v[4:7], v[144:147], v[220:223], 0
	v_mfma_f32_16x16x32_bf16 v[0:3], v[152:155], v[220:223], 0
	v_mfma_f32_16x16x32_bf16 v[52:55], v[148:151], v[188:191], v[52:55]
	v_mfma_f32_16x16x32_bf16 v[48:51], v[180:183], v[188:191], v[48:51]
	v_mfma_f32_16x16x32_bf16 v[36:39], v[148:151], v[208:211], v[36:39]
	v_mfma_f32_16x16x32_bf16 v[32:35], v[180:183], v[208:211], v[32:35]
	v_mfma_f32_16x16x32_bf16 v[20:23], v[148:151], v[216:219], v[20:23]
	v_mfma_f32_16x16x32_bf16 v[16:19], v[180:183], v[216:219], v[16:19]
	v_mfma_f32_16x16x32_bf16 v[4:7], v[148:151], v[224:227], v[4:7]
	v_mfma_f32_16x16x32_bf16 v[0:3], v[180:183], v[224:227], v[0:3]
	s_barrier
	s_add_i32 s62, 0, 0x18000
	s_add_i32 s63, 0, 0x1c000
	v_add_u32_e32 v140, s62, v201
	v_add_u32_e32 v180, s63, v201
	ds_read_b128 v[128:131], v140
	ds_read_b128 v[132:135], v140 offset:1024
	ds_read_b128 v[136:139], v140 offset:2048
	ds_read_b128 v[140:143], v140 offset:3072
	ds_read_b128 v[144:147], v180
	ds_read_b128 v[148:151], v180 offset:1024
	ds_read_b128 v[152:155], v180 offset:2048
	ds_read_b128 v[180:183], v180 offset:3072
	s_add_u32 s34, s34, s8
	s_addc_u32 s35, s35, 0
	s_mov_b32 m0, s50
	v_lshl_add_u64 v[238:239], s[34:35], 0, v[172:173]
	ds_read_b128 v[184:187], v202 offset:32768
	ds_read_b128 v[188:191], v202 offset:33792
	ds_read_b128 v[204:207], v202 offset:34816
	ds_read_b128 v[208:211], v202 offset:35840
	ds_read_b128 v[212:215], v202 offset:36864
	ds_read_b128 v[216:219], v202 offset:37888
	ds_read_b128 v[220:223], v202 offset:38912
	ds_read_b128 v[224:227], v202 offset:39936
	global_load_lds_dwordx4 v[238:239], off
	v_lshl_add_u64 v[238:239], s[34:35], 0, v[170:171]
	s_mov_b32 m0, s51
	s_nop 0
	global_load_lds_dwordx4 v[238:239], off
	s_waitcnt vmcnt(8)
	s_waitcnt lgkmcnt(0)
	s_barrier
	v_mfma_f32_16x16x32_bf16 v[124:127], v[128:131], v[184:187], v[124:127]
	v_mfma_f32_16x16x32_bf16 v[120:123], v[136:139], v[184:187], v[120:123]
	v_mfma_f32_16x16x32_bf16 v[108:111], v[128:131], v[204:207], v[108:111]
	v_mfma_f32_16x16x32_bf16 v[104:107], v[136:139], v[204:207], v[104:107]
	v_mfma_f32_16x16x32_bf16 v[92:95], v[128:131], v[212:215], v[92:95]
	v_mfma_f32_16x16x32_bf16 v[88:91], v[136:139], v[212:215], v[88:91]
	v_mfma_f32_16x16x32_bf16 v[76:79], v[128:131], v[220:223], v[76:79]
	v_mfma_f32_16x16x32_bf16 v[72:75], v[136:139], v[220:223], v[72:75]
	v_mfma_f32_16x16x32_bf16 v[124:127], v[132:135], v[188:191], v[124:127]
	v_mfma_f32_16x16x32_bf16 v[120:123], v[140:143], v[188:191], v[120:123]
	v_mfma_f32_16x16x32_bf16 v[108:111], v[132:135], v[208:211], v[108:111]
	v_mfma_f32_16x16x32_bf16 v[104:107], v[140:143], v[208:211], v[104:107]
	v_mfma_f32_16x16x32_bf16 v[92:95], v[132:135], v[216:219], v[92:95]
	v_mfma_f32_16x16x32_bf16 v[88:91], v[140:143], v[216:219], v[88:91]
	v_mfma_f32_16x16x32_bf16 v[76:79], v[132:135], v[224:227], v[76:79]
	v_mfma_f32_16x16x32_bf16 v[72:75], v[140:143], v[224:227], v[72:75]
	v_mfma_f32_16x16x32_bf16 v[116:119], v[144:147], v[184:187], v[116:119]
	v_mfma_f32_16x16x32_bf16 v[112:115], v[152:155], v[184:187], v[112:115]
	v_mfma_f32_16x16x32_bf16 v[100:103], v[144:147], v[204:207], v[100:103]
	v_mfma_f32_16x16x32_bf16 v[96:99], v[152:155], v[204:207], v[96:99]
	v_mfma_f32_16x16x32_bf16 v[84:87], v[144:147], v[212:215], v[84:87]
	v_mfma_f32_16x16x32_bf16 v[80:83], v[152:155], v[212:215], v[80:83]
	v_mfma_f32_16x16x32_bf16 v[68:71], v[144:147], v[220:223], v[68:71]
	v_mfma_f32_16x16x32_bf16 v[64:67], v[152:155], v[220:223], v[64:67]
	v_mfma_f32_16x16x32_bf16 v[116:119], v[148:151], v[188:191], v[116:119]
	v_mfma_f32_16x16x32_bf16 v[112:115], v[180:183], v[188:191], v[112:115]
	v_mfma_f32_16x16x32_bf16 v[100:103], v[148:151], v[208:211], v[100:103]
	v_mfma_f32_16x16x32_bf16 v[96:99], v[180:183], v[208:211], v[96:99]
	v_mfma_f32_16x16x32_bf16 v[84:87], v[148:151], v[216:219], v[84:87]
	v_mfma_f32_16x16x32_bf16 v[80:83], v[180:183], v[216:219], v[80:83]
	v_mfma_f32_16x16x32_bf16 v[68:71], v[148:151], v[224:227], v[68:71]
	v_mfma_f32_16x16x32_bf16 v[64:67], v[180:183], v[224:227], v[64:67]
	s_barrier
	s_add_i32 s34, s62, s47
	v_lshl_add_u64 v[192:193], v[192:193], 0, s[14:15]
	s_mov_b32 m0, s34
	ds_read_b128 v[184:187], v202 offset:49152
	ds_read_b128 v[188:191], v202 offset:50176
	ds_read_b128 v[204:207], v202 offset:51200
	ds_read_b128 v[208:211], v202 offset:52224
	ds_read_b128 v[212:215], v202 offset:53248
	ds_read_b128 v[216:219], v202 offset:54272
	ds_read_b128 v[220:223], v202 offset:55296
	ds_read_b128 v[224:227], v202 offset:56320
	global_load_lds_dwordx4 v[192:193], off
	v_lshl_add_u64 v[192:193], v[228:229], 0, s[14:15]
	s_add_i32 m0, s34, 0x2000
	s_add_i32 s34, s63, s47
	global_load_lds_dwordx4 v[192:193], off
	v_lshl_add_u64 v[192:193], v[230:231], 0, s[14:15]
	s_mov_b32 m0, s34
	s_nop 0
	global_load_lds_dwordx4 v[192:193], off
	v_lshl_add_u64 v[192:193], v[232:233], 0, s[14:15]
	s_add_i32 m0, s34, 0x2000
	s_nop 0
	global_load_lds_dwordx4 v[192:193], off
	v_lshl_add_u64 v[192:193], v[234:235], 0, s[14:15]
	s_mov_b32 m0, s60
	s_nop 0
	global_load_lds_dwordx4 v[192:193], off
	v_lshl_add_u64 v[192:193], v[236:237], 0, s[14:15]
	s_mov_b32 m0, s61
	s_nop 0
	global_load_lds_dwordx4 v[192:193], off
	s_waitcnt vmcnt(8)
	s_waitcnt lgkmcnt(0)
	s_barrier
	v_mfma_f32_16x16x32_bf16 v[60:63], v[128:131], v[184:187], v[60:63]
	v_mfma_f32_16x16x32_bf16 v[56:59], v[136:139], v[184:187], v[56:59]
	v_mfma_f32_16x16x32_bf16 v[44:47], v[128:131], v[204:207], v[44:47]
	v_mfma_f32_16x16x32_bf16 v[40:43], v[136:139], v[204:207], v[40:43]
	v_mfma_f32_16x16x32_bf16 v[28:31], v[128:131], v[212:215], v[28:31]
	v_mfma_f32_16x16x32_bf16 v[24:27], v[136:139], v[212:215], v[24:27]
	v_mfma_f32_16x16x32_bf16 v[12:15], v[128:131], v[220:223], v[12:15]
	v_mfma_f32_16x16x32_bf16 v[8:11], v[136:139], v[220:223], v[8:11]
	v_mfma_f32_16x16x32_bf16 v[60:63], v[132:135], v[188:191], v[60:63]
	v_mfma_f32_16x16x32_bf16 v[56:59], v[140:143], v[188:191], v[56:59]
	v_mfma_f32_16x16x32_bf16 v[44:47], v[132:135], v[208:211], v[44:47]
	v_mfma_f32_16x16x32_bf16 v[40:43], v[140:143], v[208:211], v[40:43]
	v_mfma_f32_16x16x32_bf16 v[28:31], v[132:135], v[216:219], v[28:31]
	v_mfma_f32_16x16x32_bf16 v[24:27], v[140:143], v[216:219], v[24:27]
	v_mfma_f32_16x16x32_bf16 v[12:15], v[132:135], v[224:227], v[12:15]
	v_mfma_f32_16x16x32_bf16 v[8:11], v[140:143], v[224:227], v[8:11]
	v_mfma_f32_16x16x32_bf16 v[52:55], v[144:147], v[184:187], v[52:55]
	v_mfma_f32_16x16x32_bf16 v[48:51], v[152:155], v[184:187], v[48:51]
	v_mfma_f32_16x16x32_bf16 v[36:39], v[144:147], v[204:207], v[36:39]
	v_mfma_f32_16x16x32_bf16 v[32:35], v[152:155], v[204:207], v[32:35]
	v_mfma_f32_16x16x32_bf16 v[20:23], v[144:147], v[212:215], v[20:23]
	v_mfma_f32_16x16x32_bf16 v[16:19], v[152:155], v[212:215], v[16:19]
	v_mfma_f32_16x16x32_bf16 v[4:7], v[144:147], v[220:223], v[4:7]
	v_mfma_f32_16x16x32_bf16 v[0:3], v[152:155], v[220:223], v[0:3]
	v_mfma_f32_16x16x32_bf16 v[52:55], v[148:151], v[188:191], v[52:55]
	v_mfma_f32_16x16x32_bf16 v[48:51], v[180:183], v[188:191], v[48:51]
	v_mfma_f32_16x16x32_bf16 v[36:39], v[148:151], v[208:211], v[36:39]
	v_mfma_f32_16x16x32_bf16 v[32:35], v[180:183], v[208:211], v[32:35]
	v_mfma_f32_16x16x32_bf16 v[20:23], v[148:151], v[216:219], v[20:23]
	v_mfma_f32_16x16x32_bf16 v[16:19], v[180:183], v[216:219], v[16:19]
	v_mfma_f32_16x16x32_bf16 v[4:7], v[148:151], v[224:227], v[4:7]
	v_mfma_f32_16x16x32_bf16 v[0:3], v[180:183], v[224:227], v[0:3]
	s_barrier
	s_add_u32 s2, s2, 0x100
	s_addc_u32 s3, s3, 0
	s_add_u32 s40, s40, 0x100
	s_addc_u32 s41, s41, 0
	s_mov_b32 s34, s86
.LBB0_497:
	s_add_i32 s86, s34, 2
	s_add_u32 s62, s2, 0x80
	s_addc_u32 s35, s3, 0
	s_add_i32 s63, 0, 0x10000
	s_cmp_eq_u32 s80, s34
	s_cselect_b32 s35, s17, s35
	s_cselect_b32 s34, s16, s62
	s_cselect_b32 s89, s25, s41
	s_cselect_b32 s88, s24, s40
	s_add_i32 s62, 0, 0x14000
	v_add_u32_e32 v140, s63, v201
	v_add_u32_e32 v180, s62, v201
	ds_read_b128 v[128:131], v140
	ds_read_b128 v[132:135], v140 offset:1024
	ds_read_b128 v[136:139], v140 offset:2048
	ds_read_b128 v[140:143], v140 offset:3072
	ds_read_b128 v[144:147], v180
	ds_read_b128 v[148:151], v180 offset:1024
	ds_read_b128 v[152:155], v180 offset:2048
	ds_read_b128 v[180:183], v180 offset:3072
	v_lshl_add_u64 v[192:193], s[2:3], 0, v[176:177]
	s_add_i32 m0, s48, 0xc000
	ds_read_b128 v[184:187], v202
	ds_read_b128 v[188:191], v202 offset:1024
	ds_read_b128 v[204:207], v202 offset:2048
	ds_read_b128 v[208:211], v202 offset:3072
	ds_read_b128 v[212:215], v202 offset:4096
	ds_read_b128 v[216:219], v202 offset:5120
	ds_read_b128 v[220:223], v202 offset:6144
	ds_read_b128 v[224:227], v202 offset:7168
	global_load_lds_dwordx4 v[192:193], off
	v_lshl_add_u64 v[192:193], s[2:3], 0, v[178:179]
	s_add_i32 m0, s48, 0xe000
	s_nop 0
	global_load_lds_dwordx4 v[192:193], off
	s_waitcnt vmcnt(8)
	s_waitcnt lgkmcnt(0)
	s_barrier
	v_mfma_f32_16x16x32_bf16 v[124:127], v[128:131], v[184:187], v[124:127]
	v_mfma_f32_16x16x32_bf16 v[120:123], v[136:139], v[184:187], v[120:123]
	v_mfma_f32_16x16x32_bf16 v[108:111], v[128:131], v[204:207], v[108:111]
	v_mfma_f32_16x16x32_bf16 v[104:107], v[136:139], v[204:207], v[104:107]
	v_mfma_f32_16x16x32_bf16 v[92:95], v[128:131], v[212:215], v[92:95]
	v_mfma_f32_16x16x32_bf16 v[88:91], v[136:139], v[212:215], v[88:91]
	v_mfma_f32_16x16x32_bf16 v[76:79], v[128:131], v[220:223], v[76:79]
	v_mfma_f32_16x16x32_bf16 v[72:75], v[136:139], v[220:223], v[72:75]
	v_mfma_f32_16x16x32_bf16 v[124:127], v[132:135], v[188:191], v[124:127]
	v_mfma_f32_16x16x32_bf16 v[120:123], v[140:143], v[188:191], v[120:123]
	v_mfma_f32_16x16x32_bf16 v[108:111], v[132:135], v[208:211], v[108:111]
	v_mfma_f32_16x16x32_bf16 v[104:107], v[140:143], v[208:211], v[104:107]
	v_mfma_f32_16x16x32_bf16 v[92:95], v[132:135], v[216:219], v[92:95]
	v_mfma_f32_16x16x32_bf16 v[88:91], v[140:143], v[216:219], v[88:91]
	v_mfma_f32_16x16x32_bf16 v[76:79], v[132:135], v[224:227], v[76:79]
	v_mfma_f32_16x16x32_bf16 v[72:75], v[140:143], v[224:227], v[72:75]
	v_mfma_f32_16x16x32_bf16 v[116:119], v[144:147], v[184:187], v[116:119]
	v_mfma_f32_16x16x32_bf16 v[112:115], v[152:155], v[184:187], v[112:115]
	v_mfma_f32_16x16x32_bf16 v[100:103], v[144:147], v[204:207], v[100:103]
	v_mfma_f32_16x16x32_bf16 v[96:99], v[152:155], v[204:207], v[96:99]
	v_mfma_f32_16x16x32_bf16 v[84:87], v[144:147], v[212:215], v[84:87]
	v_mfma_f32_16x16x32_bf16 v[80:83], v[152:155], v[212:215], v[80:83]
	v_mfma_f32_16x16x32_bf16 v[68:71], v[144:147], v[220:223], v[68:71]
	v_mfma_f32_16x16x32_bf16 v[64:67], v[152:155], v[220:223], v[64:67]
	v_mfma_f32_16x16x32_bf16 v[116:119], v[148:151], v[188:191], v[116:119]
	v_mfma_f32_16x16x32_bf16 v[112:115], v[180:183], v[188:191], v[112:115]
	v_mfma_f32_16x16x32_bf16 v[100:103], v[148:151], v[208:211], v[100:103]
	v_mfma_f32_16x16x32_bf16 v[96:99], v[180:183], v[208:211], v[96:99]
	v_mfma_f32_16x16x32_bf16 v[84:87], v[148:151], v[216:219], v[84:87]
	v_mfma_f32_16x16x32_bf16 v[80:83], v[180:183], v[216:219], v[80:83]
	v_mfma_f32_16x16x32_bf16 v[68:71], v[148:151], v[224:227], v[68:71]
	v_mfma_f32_16x16x32_bf16 v[64:67], v[180:183], v[224:227], v[64:67]
	s_barrier
	s_add_i32 s63, s63, s47
	v_lshl_add_u64 v[192:193], s[88:89], 0, v[158:159]
	s_mov_b32 m0, s63
	ds_read_b128 v[184:187], v202 offset:16384
	ds_read_b128 v[188:191], v202 offset:17408
	ds_read_b128 v[204:207], v202 offset:18432
	ds_read_b128 v[208:211], v202 offset:19456
	ds_read_b128 v[212:215], v202 offset:20480
	ds_read_b128 v[216:219], v202 offset:21504
	ds_read_b128 v[220:223], v202 offset:22528
	ds_read_b128 v[224:227], v202 offset:23552
	global_load_lds_dwordx4 v[192:193], off
	s_add_i32 m0, s63, 0x2000
	v_lshl_add_u64 v[228:229], s[88:89], 0, v[168:169]
	s_add_u32 s88, s88, s8
	s_addc_u32 s89, s89, 0
	s_add_i32 s62, s62, s47
	global_load_lds_dwordx4 v[228:229], off
	v_lshl_add_u64 v[230:231], s[88:89], 0, v[158:159]
	s_mov_b32 m0, s62
	v_lshl_add_u64 v[232:233], s[88:89], 0, v[168:169]
	global_load_lds_dwordx4 v[230:231], off
	s_add_i32 m0, s62, 0x2000
	v_lshl_add_u64 v[234:235], s[34:35], 0, v[172:173]
	global_load_lds_dwordx4 v[232:233], off
	s_mov_b32 m0, s48
	v_lshl_add_u64 v[236:237], s[34:35], 0, v[170:171]
	global_load_lds_dwordx4 v[234:235], off
	s_mov_b32 m0, s49
	s_nop 0
	global_load_lds_dwordx4 v[236:237], off
	s_waitcnt vmcnt(8)
	s_waitcnt lgkmcnt(0)
	s_barrier
	v_mfma_f32_16x16x32_bf16 v[60:63], v[128:131], v[184:187], v[60:63]
	v_mfma_f32_16x16x32_bf16 v[56:59], v[136:139], v[184:187], v[56:59]
	v_mfma_f32_16x16x32_bf16 v[44:47], v[128:131], v[204:207], v[44:47]
	v_mfma_f32_16x16x32_bf16 v[40:43], v[136:139], v[204:207], v[40:43]
	v_mfma_f32_16x16x32_bf16 v[28:31], v[128:131], v[212:215], v[28:31]
	v_mfma_f32_16x16x32_bf16 v[24:27], v[136:139], v[212:215], v[24:27]
	v_mfma_f32_16x16x32_bf16 v[12:15], v[128:131], v[220:223], v[12:15]
	v_mfma_f32_16x16x32_bf16 v[8:11], v[136:139], v[220:223], v[8:11]
	v_mfma_f32_16x16x32_bf16 v[60:63], v[132:135], v[188:191], v[60:63]
	v_mfma_f32_16x16x32_bf16 v[56:59], v[140:143], v[188:191], v[56:59]
	v_mfma_f32_16x16x32_bf16 v[44:47], v[132:135], v[208:211], v[44:47]
	v_mfma_f32_16x16x32_bf16 v[40:43], v[140:143], v[208:211], v[40:43]
	v_mfma_f32_16x16x32_bf16 v[28:31], v[132:135], v[216:219], v[28:31]
	v_mfma_f32_16x16x32_bf16 v[24:27], v[140:143], v[216:219], v[24:27]
	v_mfma_f32_16x16x32_bf16 v[12:15], v[132:135], v[224:227], v[12:15]
	v_mfma_f32_16x16x32_bf16 v[8:11], v[140:143], v[224:227], v[8:11]
	v_mfma_f32_16x16x32_bf16 v[52:55], v[144:147], v[184:187], v[52:55]
	v_mfma_f32_16x16x32_bf16 v[48:51], v[152:155], v[184:187], v[48:51]
	v_mfma_f32_16x16x32_bf16 v[36:39], v[144:147], v[204:207], v[36:39]
	v_mfma_f32_16x16x32_bf16 v[32:35], v[152:155], v[204:207], v[32:35]
	v_mfma_f32_16x16x32_bf16 v[20:23], v[144:147], v[212:215], v[20:23]
	v_mfma_f32_16x16x32_bf16 v[16:19], v[152:155], v[212:215], v[16:19]
	v_mfma_f32_16x16x32_bf16 v[4:7], v[144:147], v[220:223], v[4:7]
	v_mfma_f32_16x16x32_bf16 v[0:3], v[152:155], v[220:223], v[0:3]
	v_mfma_f32_16x16x32_bf16 v[52:55], v[148:151], v[188:191], v[52:55]
	v_mfma_f32_16x16x32_bf16 v[48:51], v[180:183], v[188:191], v[48:51]
	v_mfma_f32_16x16x32_bf16 v[36:39], v[148:151], v[208:211], v[36:39]
	v_mfma_f32_16x16x32_bf16 v[32:35], v[180:183], v[208:211], v[32:35]
	v_mfma_f32_16x16x32_bf16 v[20:23], v[148:151], v[216:219], v[20:23]
	v_mfma_f32_16x16x32_bf16 v[16:19], v[180:183], v[216:219], v[16:19]
	v_mfma_f32_16x16x32_bf16 v[4:7], v[148:151], v[224:227], v[4:7]
	v_mfma_f32_16x16x32_bf16 v[0:3], v[180:183], v[224:227], v[0:3]
	s_barrier
	s_add_i32 s62, 0, 0x18000
	s_add_i32 s63, 0, 0x1c000
	v_add_u32_e32 v140, s62, v201
	v_add_u32_e32 v180, s63, v201
	ds_read_b128 v[128:131], v140
	ds_read_b128 v[132:135], v140 offset:1024
	ds_read_b128 v[136:139], v140 offset:2048
	ds_read_b128 v[140:143], v140 offset:3072
	ds_read_b128 v[144:147], v180
	ds_read_b128 v[148:151], v180 offset:1024
	ds_read_b128 v[152:155], v180 offset:2048
	ds_read_b128 v[180:183], v180 offset:3072
	s_add_u32 s34, s34, s8
	s_addc_u32 s35, s35, 0
	s_mov_b32 m0, s50
	v_lshl_add_u64 v[238:239], s[34:35], 0, v[172:173]
	ds_read_b128 v[184:187], v202 offset:32768
	ds_read_b128 v[188:191], v202 offset:33792
	ds_read_b128 v[204:207], v202 offset:34816
	ds_read_b128 v[208:211], v202 offset:35840
	ds_read_b128 v[212:215], v202 offset:36864
	ds_read_b128 v[216:219], v202 offset:37888
	ds_read_b128 v[220:223], v202 offset:38912
	ds_read_b128 v[224:227], v202 offset:39936
	global_load_lds_dwordx4 v[238:239], off
	v_lshl_add_u64 v[238:239], s[34:35], 0, v[170:171]
	s_mov_b32 m0, s51
	s_nop 0
	global_load_lds_dwordx4 v[238:239], off
	s_waitcnt vmcnt(8)
	s_waitcnt lgkmcnt(0)
	s_barrier
	v_mfma_f32_16x16x32_bf16 v[124:127], v[128:131], v[184:187], v[124:127]
	v_mfma_f32_16x16x32_bf16 v[120:123], v[136:139], v[184:187], v[120:123]
	v_mfma_f32_16x16x32_bf16 v[108:111], v[128:131], v[204:207], v[108:111]
	v_mfma_f32_16x16x32_bf16 v[104:107], v[136:139], v[204:207], v[104:107]
	v_mfma_f32_16x16x32_bf16 v[92:95], v[128:131], v[212:215], v[92:95]
	v_mfma_f32_16x16x32_bf16 v[88:91], v[136:139], v[212:215], v[88:91]
	v_mfma_f32_16x16x32_bf16 v[76:79], v[128:131], v[220:223], v[76:79]
	v_mfma_f32_16x16x32_bf16 v[72:75], v[136:139], v[220:223], v[72:75]
	v_mfma_f32_16x16x32_bf16 v[124:127], v[132:135], v[188:191], v[124:127]
	v_mfma_f32_16x16x32_bf16 v[120:123], v[140:143], v[188:191], v[120:123]
	v_mfma_f32_16x16x32_bf16 v[108:111], v[132:135], v[208:211], v[108:111]
	v_mfma_f32_16x16x32_bf16 v[104:107], v[140:143], v[208:211], v[104:107]
	v_mfma_f32_16x16x32_bf16 v[92:95], v[132:135], v[216:219], v[92:95]
	v_mfma_f32_16x16x32_bf16 v[88:91], v[140:143], v[216:219], v[88:91]
	v_mfma_f32_16x16x32_bf16 v[76:79], v[132:135], v[224:227], v[76:79]
	v_mfma_f32_16x16x32_bf16 v[72:75], v[140:143], v[224:227], v[72:75]
	v_mfma_f32_16x16x32_bf16 v[116:119], v[144:147], v[184:187], v[116:119]
	v_mfma_f32_16x16x32_bf16 v[112:115], v[152:155], v[184:187], v[112:115]
	v_mfma_f32_16x16x32_bf16 v[100:103], v[144:147], v[204:207], v[100:103]
	v_mfma_f32_16x16x32_bf16 v[96:99], v[152:155], v[204:207], v[96:99]
	v_mfma_f32_16x16x32_bf16 v[84:87], v[144:147], v[212:215], v[84:87]
	v_mfma_f32_16x16x32_bf16 v[80:83], v[152:155], v[212:215], v[80:83]
	v_mfma_f32_16x16x32_bf16 v[68:71], v[144:147], v[220:223], v[68:71]
	v_mfma_f32_16x16x32_bf16 v[64:67], v[152:155], v[220:223], v[64:67]
	v_mfma_f32_16x16x32_bf16 v[116:119], v[148:151], v[188:191], v[116:119]
	v_mfma_f32_16x16x32_bf16 v[112:115], v[180:183], v[188:191], v[112:115]
	v_mfma_f32_16x16x32_bf16 v[100:103], v[148:151], v[208:211], v[100:103]
	v_mfma_f32_16x16x32_bf16 v[96:99], v[180:183], v[208:211], v[96:99]
	v_mfma_f32_16x16x32_bf16 v[84:87], v[148:151], v[216:219], v[84:87]
	v_mfma_f32_16x16x32_bf16 v[80:83], v[180:183], v[216:219], v[80:83]
	v_mfma_f32_16x16x32_bf16 v[68:71], v[148:151], v[224:227], v[68:71]
	v_mfma_f32_16x16x32_bf16 v[64:67], v[180:183], v[224:227], v[64:67]
	s_barrier
	s_add_i32 s34, s62, s47
	v_lshl_add_u64 v[192:193], v[192:193], 0, s[14:15]
	s_mov_b32 m0, s34
	ds_read_b128 v[184:187], v202 offset:49152
	ds_read_b128 v[188:191], v202 offset:50176
	ds_read_b128 v[204:207], v202 offset:51200
	ds_read_b128 v[208:211], v202 offset:52224
	ds_read_b128 v[212:215], v202 offset:53248
	ds_read_b128 v[216:219], v202 offset:54272
	ds_read_b128 v[220:223], v202 offset:55296
	ds_read_b128 v[224:227], v202 offset:56320
	global_load_lds_dwordx4 v[192:193], off
	v_lshl_add_u64 v[192:193], v[228:229], 0, s[14:15]
	s_add_i32 m0, s34, 0x2000
	s_add_i32 s34, s63, s47
	global_load_lds_dwordx4 v[192:193], off
	v_lshl_add_u64 v[192:193], v[230:231], 0, s[14:15]
	s_mov_b32 m0, s34
	s_nop 0
	global_load_lds_dwordx4 v[192:193], off
	v_lshl_add_u64 v[192:193], v[232:233], 0, s[14:15]
	s_add_i32 m0, s34, 0x2000
	s_nop 0
	global_load_lds_dwordx4 v[192:193], off
	v_lshl_add_u64 v[192:193], v[234:235], 0, s[14:15]
	s_mov_b32 m0, s60
	s_nop 0
	global_load_lds_dwordx4 v[192:193], off
	v_lshl_add_u64 v[192:193], v[236:237], 0, s[14:15]
	s_mov_b32 m0, s61
	s_nop 0
	global_load_lds_dwordx4 v[192:193], off
	s_waitcnt vmcnt(8)
	s_waitcnt lgkmcnt(0)
	s_barrier
	v_mfma_f32_16x16x32_bf16 v[60:63], v[128:131], v[184:187], v[60:63]
	v_mfma_f32_16x16x32_bf16 v[56:59], v[136:139], v[184:187], v[56:59]
	v_mfma_f32_16x16x32_bf16 v[44:47], v[128:131], v[204:207], v[44:47]
	v_mfma_f32_16x16x32_bf16 v[40:43], v[136:139], v[204:207], v[40:43]
	v_mfma_f32_16x16x32_bf16 v[28:31], v[128:131], v[212:215], v[28:31]
	v_mfma_f32_16x16x32_bf16 v[24:27], v[136:139], v[212:215], v[24:27]
	v_mfma_f32_16x16x32_bf16 v[12:15], v[128:131], v[220:223], v[12:15]
	v_mfma_f32_16x16x32_bf16 v[8:11], v[136:139], v[220:223], v[8:11]
	v_mfma_f32_16x16x32_bf16 v[60:63], v[132:135], v[188:191], v[60:63]
	v_mfma_f32_16x16x32_bf16 v[56:59], v[140:143], v[188:191], v[56:59]
	v_mfma_f32_16x16x32_bf16 v[44:47], v[132:135], v[208:211], v[44:47]
	v_mfma_f32_16x16x32_bf16 v[40:43], v[140:143], v[208:211], v[40:43]
	v_mfma_f32_16x16x32_bf16 v[28:31], v[132:135], v[216:219], v[28:31]
	v_mfma_f32_16x16x32_bf16 v[24:27], v[140:143], v[216:219], v[24:27]
	v_mfma_f32_16x16x32_bf16 v[12:15], v[132:135], v[224:227], v[12:15]
	v_mfma_f32_16x16x32_bf16 v[8:11], v[140:143], v[224:227], v[8:11]
	v_mfma_f32_16x16x32_bf16 v[52:55], v[144:147], v[184:187], v[52:55]
	v_mfma_f32_16x16x32_bf16 v[48:51], v[152:155], v[184:187], v[48:51]
	v_mfma_f32_16x16x32_bf16 v[36:39], v[144:147], v[204:207], v[36:39]
	v_mfma_f32_16x16x32_bf16 v[32:35], v[152:155], v[204:207], v[32:35]
	v_mfma_f32_16x16x32_bf16 v[20:23], v[144:147], v[212:215], v[20:23]
	v_mfma_f32_16x16x32_bf16 v[16:19], v[152:155], v[212:215], v[16:19]
	v_mfma_f32_16x16x32_bf16 v[4:7], v[144:147], v[220:223], v[4:7]
	v_mfma_f32_16x16x32_bf16 v[0:3], v[152:155], v[220:223], v[0:3]
	v_mfma_f32_16x16x32_bf16 v[52:55], v[148:151], v[188:191], v[52:55]
	v_mfma_f32_16x16x32_bf16 v[48:51], v[180:183], v[188:191], v[48:51]
	v_mfma_f32_16x16x32_bf16 v[36:39], v[148:151], v[208:211], v[36:39]
	v_mfma_f32_16x16x32_bf16 v[32:35], v[180:183], v[208:211], v[32:35]
	v_mfma_f32_16x16x32_bf16 v[20:23], v[148:151], v[216:219], v[20:23]
	v_mfma_f32_16x16x32_bf16 v[16:19], v[180:183], v[216:219], v[16:19]
	v_mfma_f32_16x16x32_bf16 v[4:7], v[148:151], v[224:227], v[4:7]
	v_mfma_f32_16x16x32_bf16 v[0:3], v[180:183], v[224:227], v[0:3]
	s_barrier
	s_add_u32 s2, s2, 0x100
	s_addc_u32 s3, s3, 0
	s_add_u32 s40, s40, 0x100
	s_addc_u32 s41, s41, 0
	s_cmp_ge_u32 s86, s64
	s_mov_b32 s34, s86
	s_cbranch_scc0 .LBB0_497
	s_and_b64 vcc, exec, s[12:13]
	s_cbranch_vccz .LBB0_500
	s_barrier

.LBB0_519:
	s_setprio 0
	s_waitcnt vmcnt(0)
	s_barrier
	s_mov_b32 s51, s87

.LBB0_623:
	s_lshl_b32 s2, s6, 5
	s_and_b32 s75, s2, 0x60
	s_lshl_b32 s65, s5, 6
	s_lshl_b32 s5, s5, 13
	s_lshl_b32 s6, s75, 7
	s_waitcnt vmcnt(8)
	s_barrier
	v_bfe_u32 v171, v8, 4, 2
	v_and_b32_e32 v170, 15, v8
	v_lshlrev_b32_e32 v0, 4, v171
	v_lshlrev_b32_e32 v1, 2, v8
	v_lshl_or_b32 v0, v170, 6, v0
	v_and_b32_e32 v1, 32, v1
	v_bitop3_b32 v2, v0, s5, v1 bitop3:0xde
	s_nop 0
	v_lshlrev_b32_e32 v0, 14, v9
	v_and_b32_e32 v0, 0xffff8000, v0
	v_lshl_add_u32 v0, v10, 11, v0
	v_and_b32_e32 v1, 1, v9
	v_lshl_or_b32 v0, v1, 6, v0
	v_lshl_add_u32 v140, v11, 1, v0
	v_lshlrev_b32_e32 v0, 14, v12
	v_and_b32_e32 v0, 0xffff8000, v0
	s_waitcnt vmcnt(6)
	v_lshl_add_u32 v0, v13, 11, v0
	v_and_b32_e32 v1, 1, v12
	s_cmpk_lt_u32 s4, 0x100
	v_lshl_or_b32 v0, v1, 6, v0
	s_cselect_b64 s[2:3], -1, 0
	s_or_b32 s79, s75, 0xffffea00
	v_mov_b32_e32 v141, v159
	v_lshl_add_u32 v142, v14, 1, v0
	v_mov_b32_e32 v143, v159
	s_mov_b32 s17, 0
	s_nop 0
	s_mov_b32 s80, 0
	s_barrier
	s_and_b64 vcc, exec, s[2:3]
	s_cbranch_vccnz .Lprio_sw_done
	s_setprio 1

.LBB0_628:
	s_ashr_i32 s13, s12, 31
	s_lshl_b64 s[6:7], s[12:13], 19
	s_add_u32 s6, s30, s6
	s_addc_u32 s7, s31, s7
	s_and_b64 s[24:25], s[38:39], exec
	s_cselect_b32 s13, s7, s35
	s_cselect_b32 s29, s6, s34
	s_ashr_i32 s5, s4, 31
	s_lshl_b64 s[24:25], s[4:5], 19
	s_add_u32 s24, s49, s24
	s_addc_u32 s25, s50, s25
	s_and_b64 s[42:43], s[38:39], exec
	s_cselect_b32 s5, s25, s41
	s_cselect_b32 s82, s24, s40
	s_add_u32 s34, s34, 0x40080
	s_addc_u32 s35, s35, 0
	s_add_u32 s83, s40, 0x100
	s_addc_u32 s84, s41, 0
	s_mov_b32 s85, -2
	s_add_u32 s40, s34, 0xfffc0080
	s_addc_u32 s41, s35, -1
	s_add_i32 s62, 0, 0x10000
	s_cmp_eq_u32 s85, 12
	s_cselect_b32 s43, s13, s41
	s_cselect_b32 s42, s29, s40
	s_cselect_b32 s41, s5, s84
	s_cselect_b32 s40, s82, s83
	s_add_i32 s63, 0, 0x14000
	s_add_u32 s86, s34, 0xfffc0000
	s_addc_u32 s87, s35, -1
	s_mov_b32 m0, s76
	v_add_u32_e32 v152, s62, v172
	v_add_u32_e32 v158, s63, v172
	v_add_u32_e32 v245, s62, v243
	v_add_u32_e32 v246, s63, v243
	global_load_lds_dwordx4 v132, s[86:87]
	s_mov_b32 m0, s77
	ds_read_b128 v[128:131], v152
	global_load_lds_dwordx4 v136, s[86:87]
	ds_read_b128 v[144:147], v245
	ds_read_b128 v[148:151], v152 offset:2048
	ds_read_b128 v[152:155], v245 offset:2048
	ds_read_b128 v[174:177], v158
	ds_read_b128 v[178:181], v246
	ds_read_b128 v[182:185], v158 offset:2048
	ds_read_b128 v[186:189], v246 offset:2048
	ds_read_b128 v[190:193], v173
	ds_read_b128 v[198:201], v244
	ds_read_b128 v[202:205], v173 offset:2048
	ds_read_b128 v[206:209], v244 offset:2048
	ds_read_b128 v[210:213], v173 offset:4096
	ds_read_b128 v[214:217], v244 offset:4096
	ds_read_b128 v[218:221], v173 offset:6144
	ds_read_b128 v[222:225], v244 offset:6144
	s_waitcnt vmcnt(6)
	s_waitcnt lgkmcnt(0)
	s_barrier
	v_mfma_f32_16x16x32_bf16 v[124:127], v[128:131], v[190:193], 0
	v_mfma_f32_16x16x32_bf16 v[116:119], v[148:151], v[190:193], 0
	v_mfma_f32_16x16x32_bf16 v[108:111], v[128:131], v[202:205], 0
	s_add_i32 m0, s51, 0xc000
	v_mfma_f32_16x16x32_bf16 v[100:103], v[148:151], v[202:205], 0
	v_mfma_f32_16x16x32_bf16 v[92:95], v[128:131], v[210:213], 0
	global_load_lds_dwordx4 v132, s[34:35]
	v_mfma_f32_16x16x32_bf16 v[84:87], v[148:151], v[210:213], 0
	v_mfma_f32_16x16x32_bf16 v[76:79], v[128:131], v[218:221], 0
	v_mfma_f32_16x16x32_bf16 v[68:71], v[148:151], v[218:221], 0
	v_mfma_f32_16x16x32_bf16 v[124:127], v[144:147], v[198:201], v[124:127]
	v_mfma_f32_16x16x32_bf16 v[116:119], v[152:155], v[198:201], v[116:119]
	v_mfma_f32_16x16x32_bf16 v[108:111], v[144:147], v[206:209], v[108:111]
	s_add_i32 m0, s51, 0xe000
	v_mfma_f32_16x16x32_bf16 v[100:103], v[152:155], v[206:209], v[100:103]
	v_mfma_f32_16x16x32_bf16 v[92:95], v[144:147], v[214:217], v[92:95]
	global_load_lds_dwordx4 v136, s[34:35]
	v_mfma_f32_16x16x32_bf16 v[84:87], v[152:155], v[214:217], v[84:87]
	v_mfma_f32_16x16x32_bf16 v[76:79], v[144:147], v[222:225], v[76:79]
	v_mfma_f32_16x16x32_bf16 v[68:71], v[152:155], v[222:225], v[68:71]
	v_mfma_f32_16x16x32_bf16 v[120:123], v[174:177], v[190:193], 0
	v_mfma_f32_16x16x32_bf16 v[112:115], v[182:185], v[190:193], 0
	v_mfma_f32_16x16x32_bf16 v[104:107], v[174:177], v[202:205], 0
	v_mfma_f32_16x16x32_bf16 v[96:99], v[182:185], v[202:205], 0
	v_mfma_f32_16x16x32_bf16 v[88:91], v[174:177], v[210:213], 0
	v_mfma_f32_16x16x32_bf16 v[80:83], v[182:185], v[210:213], 0
	v_mfma_f32_16x16x32_bf16 v[72:75], v[174:177], v[218:221], 0
	v_mfma_f32_16x16x32_bf16 v[64:67], v[182:185], v[218:221], 0
	v_mfma_f32_16x16x32_bf16 v[120:123], v[178:181], v[198:201], v[120:123]
	v_mfma_f32_16x16x32_bf16 v[112:115], v[186:189], v[198:201], v[112:115]
	v_mfma_f32_16x16x32_bf16 v[104:107], v[178:181], v[206:209], v[104:107]
	v_mfma_f32_16x16x32_bf16 v[96:99], v[186:189], v[206:209], v[96:99]
	v_mfma_f32_16x16x32_bf16 v[88:91], v[178:181], v[214:217], v[88:91]
	v_mfma_f32_16x16x32_bf16 v[80:83], v[186:189], v[214:217], v[80:83]
	v_mfma_f32_16x16x32_bf16 v[72:75], v[178:181], v[222:225], v[72:75]
	v_mfma_f32_16x16x32_bf16 v[64:67], v[186:189], v[222:225], v[64:67]
	s_barrier
	s_add_i32 s62, s62, s48
	s_mov_b32 m0, s62
	ds_read_b128 v[190:193], v173 offset:16384
	global_load_lds_dwordx4 v134, s[40:41]
	s_add_i32 m0, s62, 0x2000
	ds_read_b128 v[198:201], v244 offset:16384
	global_load_lds_dwordx4 v138, s[40:41]
	ds_read_b128 v[202:205], v173 offset:18432
	ds_read_b128 v[206:209], v244 offset:18432
	ds_read_b128 v[210:213], v173 offset:20480
	ds_read_b128 v[214:217], v244 offset:20480
	ds_read_b128 v[218:221], v173 offset:22528
	ds_read_b128 v[222:225], v244 offset:22528
	s_add_u32 s86, s40, 0x40000
	s_addc_u32 s87, s41, 0
	s_add_i32 s62, s63, s48
	s_waitcnt vmcnt(4)
	s_waitcnt lgkmcnt(0)
	s_barrier
	v_mfma_f32_16x16x32_bf16 v[60:63], v[128:131], v[190:193], 0
	v_mfma_f32_16x16x32_bf16 v[52:55], v[148:151], v[190:193], 0
	v_mfma_f32_16x16x32_bf16 v[44:47], v[128:131], v[202:205], 0
	s_mov_b32 m0, s62
	v_mfma_f32_16x16x32_bf16 v[36:39], v[148:151], v[202:205], 0
	v_mfma_f32_16x16x32_bf16 v[28:31], v[128:131], v[210:213], 0
	global_load_lds_dwordx4 v134, s[86:87]
	v_mfma_f32_16x16x32_bf16 v[20:23], v[148:151], v[210:213], 0
	v_mfma_f32_16x16x32_bf16 v[8:11], v[128:131], v[218:221], 0
	v_mfma_f32_16x16x32_bf16 v[4:7], v[148:151], v[218:221], 0
	v_mfma_f32_16x16x32_bf16 v[60:63], v[144:147], v[198:201], v[60:63]
	v_mfma_f32_16x16x32_bf16 v[52:55], v[152:155], v[198:201], v[52:55]
	v_mfma_f32_16x16x32_bf16 v[44:47], v[144:147], v[206:209], v[44:47]
	s_add_i32 m0, s62, 0x2000
	v_mfma_f32_16x16x32_bf16 v[36:39], v[152:155], v[206:209], v[36:39]
	v_mfma_f32_16x16x32_bf16 v[28:31], v[144:147], v[214:217], v[28:31]
	global_load_lds_dwordx4 v138, s[86:87]
	v_mfma_f32_16x16x32_bf16 v[20:23], v[152:155], v[214:217], v[20:23]
	v_mfma_f32_16x16x32_bf16 v[8:11], v[144:147], v[222:225], v[8:11]
	v_mfma_f32_16x16x32_bf16 v[4:7], v[152:155], v[222:225], v[4:7]
	v_mfma_f32_16x16x32_bf16 v[56:59], v[174:177], v[190:193], 0
	v_mfma_f32_16x16x32_bf16 v[48:51], v[182:185], v[190:193], 0
	v_mfma_f32_16x16x32_bf16 v[40:43], v[174:177], v[202:205], 0
	v_mfma_f32_16x16x32_bf16 v[32:35], v[182:185], v[202:205], 0
	v_mfma_f32_16x16x32_bf16 v[24:27], v[174:177], v[210:213], 0
	v_mfma_f32_16x16x32_bf16 v[16:19], v[182:185], v[210:213], 0
	v_mfma_f32_16x16x32_bf16 v[12:15], v[174:177], v[218:221], 0
	v_mfma_f32_16x16x32_bf16 v[0:3], v[182:185], v[218:221], 0
	v_mfma_f32_16x16x32_bf16 v[56:59], v[178:181], v[198:201], v[56:59]
	v_mfma_f32_16x16x32_bf16 v[48:51], v[186:189], v[198:201], v[48:51]
	v_mfma_f32_16x16x32_bf16 v[40:43], v[178:181], v[206:209], v[40:43]
	v_mfma_f32_16x16x32_bf16 v[32:35], v[186:189], v[206:209], v[32:35]
	v_mfma_f32_16x16x32_bf16 v[24:27], v[178:181], v[214:217], v[24:27]
	v_mfma_f32_16x16x32_bf16 v[16:19], v[186:189], v[214:217], v[16:19]
	v_mfma_f32_16x16x32_bf16 v[12:15], v[178:181], v[222:225], v[12:15]
	v_mfma_f32_16x16x32_bf16 v[0:3], v[186:189], v[222:225], v[0:3]
	s_barrier
	s_add_i32 s62, 0, 0x18000
	s_add_i32 s63, 0, 0x1c000
	s_mov_b32 m0, s51
	v_add_u32_e32 v152, s62, v172
	v_add_u32_e32 v158, s63, v172
	v_add_u32_e32 v245, s62, v243
	v_add_u32_e32 v246, s63, v243
	global_load_lds_dwordx4 v132, s[42:43]
	s_mov_b32 m0, s60
	ds_read_b128 v[128:131], v152
	global_load_lds_dwordx4 v136, s[42:43]
	ds_read_b128 v[144:147], v245
	ds_read_b128 v[148:151], v152 offset:2048
	ds_read_b128 v[152:155], v245 offset:2048
	ds_read_b128 v[174:177], v158
	ds_read_b128 v[178:181], v246
	ds_read_b128 v[182:185], v158 offset:2048
	ds_read_b128 v[186:189], v246 offset:2048
	ds_read_b128 v[190:193], v173 offset:32768
	ds_read_b128 v[198:201], v244 offset:32768
	ds_read_b128 v[202:205], v173 offset:34816
	ds_read_b128 v[206:209], v244 offset:34816
	ds_read_b128 v[210:213], v173 offset:36864
	ds_read_b128 v[214:217], v244 offset:36864
	ds_read_b128 v[218:221], v173 offset:38912
	ds_read_b128 v[222:225], v244 offset:38912
	s_add_u32 s42, s42, 0x40000
	s_addc_u32 s43, s43, 0
	s_waitcnt vmcnt(6)
	s_waitcnt lgkmcnt(0)
	s_barrier
	v_mfma_f32_16x16x32_bf16 v[124:127], v[128:131], v[190:193], v[124:127]
	v_mfma_f32_16x16x32_bf16 v[116:119], v[148:151], v[190:193], v[116:119]
	v_mfma_f32_16x16x32_bf16 v[108:111], v[128:131], v[202:205], v[108:111]
	s_mov_b32 m0, s61
	v_mfma_f32_16x16x32_bf16 v[100:103], v[148:151], v[202:205], v[100:103]
	v_mfma_f32_16x16x32_bf16 v[92:95], v[128:131], v[210:213], v[92:95]
	global_load_lds_dwordx4 v132, s[42:43]
	v_mfma_f32_16x16x32_bf16 v[84:87], v[148:151], v[210:213], v[84:87]
	v_mfma_f32_16x16x32_bf16 v[76:79], v[128:131], v[218:221], v[76:79]
	v_mfma_f32_16x16x32_bf16 v[68:71], v[148:151], v[218:221], v[68:71]
	v_mfma_f32_16x16x32_bf16 v[124:127], v[144:147], v[198:201], v[124:127]
	v_mfma_f32_16x16x32_bf16 v[116:119], v[152:155], v[198:201], v[116:119]
	v_mfma_f32_16x16x32_bf16 v[108:111], v[144:147], v[206:209], v[108:111]
	s_mov_b32 m0, s64
	v_mfma_f32_16x16x32_bf16 v[100:103], v[152:155], v[206:209], v[100:103]
	v_mfma_f32_16x16x32_bf16 v[92:95], v[144:147], v[214:217], v[92:95]
	global_load_lds_dwordx4 v136, s[42:43]
	v_mfma_f32_16x16x32_bf16 v[84:87], v[152:155], v[214:217], v[84:87]
	v_mfma_f32_16x16x32_bf16 v[76:79], v[144:147], v[222:225], v[76:79]
	v_mfma_f32_16x16x32_bf16 v[68:71], v[152:155], v[222:225], v[68:71]
	v_mfma_f32_16x16x32_bf16 v[120:123], v[174:177], v[190:193], v[120:123]
	v_mfma_f32_16x16x32_bf16 v[112:115], v[182:185], v[190:193], v[112:115]
	v_mfma_f32_16x16x32_bf16 v[104:107], v[174:177], v[202:205], v[104:107]
	v_mfma_f32_16x16x32_bf16 v[96:99], v[182:185], v[202:205], v[96:99]
	v_mfma_f32_16x16x32_bf16 v[88:91], v[174:177], v[210:213], v[88:91]
	v_mfma_f32_16x16x32_bf16 v[80:83], v[182:185], v[210:213], v[80:83]
	v_mfma_f32_16x16x32_bf16 v[72:75], v[174:177], v[218:221], v[72:75]
	v_mfma_f32_16x16x32_bf16 v[64:67], v[182:185], v[218:221], v[64:67]
	v_mfma_f32_16x16x32_bf16 v[120:123], v[178:181], v[198:201], v[120:123]
	v_mfma_f32_16x16x32_bf16 v[112:115], v[186:189], v[198:201], v[112:115]
	v_mfma_f32_16x16x32_bf16 v[104:107], v[178:181], v[206:209], v[104:107]
	v_mfma_f32_16x16x32_bf16 v[96:99], v[186:189], v[206:209], v[96:99]
	v_mfma_f32_16x16x32_bf16 v[88:91], v[178:181], v[214:217], v[88:91]
	v_mfma_f32_16x16x32_bf16 v[80:83], v[186:189], v[214:217], v[80:83]
	v_mfma_f32_16x16x32_bf16 v[72:75], v[178:181], v[222:225], v[72:75]
	v_mfma_f32_16x16x32_bf16 v[64:67], v[186:189], v[222:225], v[64:67]
	s_barrier
	s_add_i32 s42, s62, s48
	s_add_u32 s40, s40, 0x80
	s_addc_u32 s41, s41, 0
	s_mov_b32 m0, s42
	ds_read_b128 v[190:193], v173 offset:49152
	global_load_lds_dwordx4 v134, s[40:41]
	s_add_i32 m0, s42, 0x2000
	ds_read_b128 v[198:201], v244 offset:49152
	global_load_lds_dwordx4 v138, s[40:41]
	ds_read_b128 v[202:205], v173 offset:51200
	ds_read_b128 v[206:209], v244 offset:51200
	ds_read_b128 v[210:213], v173 offset:53248
	ds_read_b128 v[214:217], v244 offset:53248
	ds_read_b128 v[218:221], v173 offset:55296
	ds_read_b128 v[222:225], v244 offset:55296
	s_add_u32 s40, s40, 0x40000
	s_addc_u32 s41, s41, 0
	s_add_i32 s42, s63, s48
	s_waitcnt vmcnt(4)
	s_waitcnt lgkmcnt(0)
	s_barrier
	v_mfma_f32_16x16x32_bf16 v[60:63], v[128:131], v[190:193], v[60:63]
	v_mfma_f32_16x16x32_bf16 v[52:55], v[148:151], v[190:193], v[52:55]
	v_mfma_f32_16x16x32_bf16 v[44:47], v[128:131], v[202:205], v[44:47]
	s_mov_b32 m0, s42
	v_mfma_f32_16x16x32_bf16 v[36:39], v[148:151], v[202:205], v[36:39]
	v_mfma_f32_16x16x32_bf16 v[28:31], v[128:131], v[210:213], v[28:31]
	global_load_lds_dwordx4 v134, s[40:41]
	v_mfma_f32_16x16x32_bf16 v[20:23], v[148:151], v[210:213], v[20:23]
	v_mfma_f32_16x16x32_bf16 v[8:11], v[128:131], v[218:221], v[8:11]
	v_mfma_f32_16x16x32_bf16 v[4:7], v[148:151], v[218:221], v[4:7]
	v_mfma_f32_16x16x32_bf16 v[60:63], v[144:147], v[198:201], v[60:63]
	v_mfma_f32_16x16x32_bf16 v[52:55], v[152:155], v[198:201], v[52:55]
	v_mfma_f32_16x16x32_bf16 v[44:47], v[144:147], v[206:209], v[44:47]
	s_add_i32 m0, s42, 0x2000
	v_mfma_f32_16x16x32_bf16 v[36:39], v[152:155], v[206:209], v[36:39]
	v_mfma_f32_16x16x32_bf16 v[28:31], v[144:147], v[214:217], v[28:31]
	global_load_lds_dwordx4 v138, s[40:41]
	v_mfma_f32_16x16x32_bf16 v[20:23], v[152:155], v[214:217], v[20:23]
	v_mfma_f32_16x16x32_bf16 v[8:11], v[144:147], v[222:225], v[8:11]
	v_mfma_f32_16x16x32_bf16 v[4:7], v[152:155], v[222:225], v[4:7]
	v_mfma_f32_16x16x32_bf16 v[56:59], v[174:177], v[190:193], v[56:59]
	v_mfma_f32_16x16x32_bf16 v[48:51], v[182:185], v[190:193], v[48:51]
	v_mfma_f32_16x16x32_bf16 v[40:43], v[174:177], v[202:205], v[40:43]
	v_mfma_f32_16x16x32_bf16 v[32:35], v[182:185], v[202:205], v[32:35]
	v_mfma_f32_16x16x32_bf16 v[24:27], v[174:177], v[210:213], v[24:27]
	v_mfma_f32_16x16x32_bf16 v[16:19], v[182:185], v[210:213], v[16:19]
	v_mfma_f32_16x16x32_bf16 v[12:15], v[174:177], v[218:221], v[12:15]
	v_mfma_f32_16x16x32_bf16 v[0:3], v[182:185], v[218:221], v[0:3]
	v_mfma_f32_16x16x32_bf16 v[56:59], v[178:181], v[198:201], v[56:59]
	v_mfma_f32_16x16x32_bf16 v[48:51], v[186:189], v[198:201], v[48:51]
	v_mfma_f32_16x16x32_bf16 v[40:43], v[178:181], v[206:209], v[40:43]
	v_mfma_f32_16x16x32_bf16 v[32:35], v[186:189], v[206:209], v[32:35]
	v_mfma_f32_16x16x32_bf16 v[24:27], v[178:181], v[214:217], v[24:27]
	v_mfma_f32_16x16x32_bf16 v[16:19], v[186:189], v[214:217], v[16:19]
	v_mfma_f32_16x16x32_bf16 v[12:15], v[178:181], v[222:225], v[12:15]
	v_mfma_f32_16x16x32_bf16 v[0:3], v[186:189], v[222:225], v[0:3]
	s_barrier
	s_add_i32 s85, s85, 2
	s_add_u32 s34, s34, 0x100
	s_addc_u32 s35, s35, 0
	s_add_u32 s83, s83, 0x100
	s_addc_u32 s84, s84, 0
.LBB0_629:
	s_add_u32 s40, s34, 0xfffc0080
	s_addc_u32 s41, s35, -1
	s_add_i32 s62, 0, 0x10000
	s_cmp_eq_u32 s85, 12
	s_cselect_b32 s43, s13, s41
	s_cselect_b32 s42, s29, s40
	s_cselect_b32 s41, s5, s84
	s_cselect_b32 s40, s82, s83
	s_add_i32 s63, 0, 0x14000
	s_add_u32 s86, s34, 0xfffc0000
	s_addc_u32 s87, s35, -1
	s_mov_b32 m0, s76
	v_add_u32_e32 v152, s62, v172
	v_add_u32_e32 v158, s63, v172
	v_add_u32_e32 v245, s62, v243
	v_add_u32_e32 v246, s63, v243
	global_load_lds_dwordx4 v132, s[86:87]
	s_mov_b32 m0, s77
	ds_read_b128 v[128:131], v152
	global_load_lds_dwordx4 v136, s[86:87]
	ds_read_b128 v[144:147], v245
	ds_read_b128 v[148:151], v152 offset:2048
	ds_read_b128 v[152:155], v245 offset:2048
	ds_read_b128 v[174:177], v158
	ds_read_b128 v[178:181], v246
	ds_read_b128 v[182:185], v158 offset:2048
	ds_read_b128 v[186:189], v246 offset:2048
	ds_read_b128 v[190:193], v173
	ds_read_b128 v[198:201], v244
	ds_read_b128 v[202:205], v173 offset:2048
	ds_read_b128 v[206:209], v244 offset:2048
	ds_read_b128 v[210:213], v173 offset:4096
	ds_read_b128 v[214:217], v244 offset:4096
	ds_read_b128 v[218:221], v173 offset:6144
	ds_read_b128 v[222:225], v244 offset:6144
	s_waitcnt vmcnt(6)
	s_waitcnt lgkmcnt(0)
	s_barrier
	v_mfma_f32_16x16x32_bf16 v[124:127], v[128:131], v[190:193], v[124:127]
	v_mfma_f32_16x16x32_bf16 v[116:119], v[148:151], v[190:193], v[116:119]
	v_mfma_f32_16x16x32_bf16 v[108:111], v[128:131], v[202:205], v[108:111]
	s_add_i32 m0, s51, 0xc000
	v_mfma_f32_16x16x32_bf16 v[100:103], v[148:151], v[202:205], v[100:103]
	v_mfma_f32_16x16x32_bf16 v[92:95], v[128:131], v[210:213], v[92:95]
	global_load_lds_dwordx4 v132, s[34:35]
	v_mfma_f32_16x16x32_bf16 v[84:87], v[148:151], v[210:213], v[84:87]
	v_mfma_f32_16x16x32_bf16 v[76:79], v[128:131], v[218:221], v[76:79]
	v_mfma_f32_16x16x32_bf16 v[68:71], v[148:151], v[218:221], v[68:71]
	v_mfma_f32_16x16x32_bf16 v[124:127], v[144:147], v[198:201], v[124:127]
	v_mfma_f32_16x16x32_bf16 v[116:119], v[152:155], v[198:201], v[116:119]
	v_mfma_f32_16x16x32_bf16 v[108:111], v[144:147], v[206:209], v[108:111]
	s_add_i32 m0, s51, 0xe000
	v_mfma_f32_16x16x32_bf16 v[100:103], v[152:155], v[206:209], v[100:103]
	v_mfma_f32_16x16x32_bf16 v[92:95], v[144:147], v[214:217], v[92:95]
	global_load_lds_dwordx4 v136, s[34:35]
	v_mfma_f32_16x16x32_bf16 v[84:87], v[152:155], v[214:217], v[84:87]
	v_mfma_f32_16x16x32_bf16 v[76:79], v[144:147], v[222:225], v[76:79]
	v_mfma_f32_16x16x32_bf16 v[68:71], v[152:155], v[222:225], v[68:71]
	v_mfma_f32_16x16x32_bf16 v[120:123], v[174:177], v[190:193], v[120:123]
	v_mfma_f32_16x16x32_bf16 v[112:115], v[182:185], v[190:193], v[112:115]
	v_mfma_f32_16x16x32_bf16 v[104:107], v[174:177], v[202:205], v[104:107]
	v_mfma_f32_16x16x32_bf16 v[96:99], v[182:185], v[202:205], v[96:99]
	v_mfma_f32_16x16x32_bf16 v[88:91], v[174:177], v[210:213], v[88:91]
	v_mfma_f32_16x16x32_bf16 v[80:83], v[182:185], v[210:213], v[80:83]
	v_mfma_f32_16x16x32_bf16 v[72:75], v[174:177], v[218:221], v[72:75]
	v_mfma_f32_16x16x32_bf16 v[64:67], v[182:185], v[218:221], v[64:67]
	v_mfma_f32_16x16x32_bf16 v[120:123], v[178:181], v[198:201], v[120:123]
	v_mfma_f32_16x16x32_bf16 v[112:115], v[186:189], v[198:201], v[112:115]
	v_mfma_f32_16x16x32_bf16 v[104:107], v[178:181], v[206:209], v[104:107]
	v_mfma_f32_16x16x32_bf16 v[96:99], v[186:189], v[206:209], v[96:99]
	v_mfma_f32_16x16x32_bf16 v[88:91], v[178:181], v[214:217], v[88:91]
	v_mfma_f32_16x16x32_bf16 v[80:83], v[186:189], v[214:217], v[80:83]
	v_mfma_f32_16x16x32_bf16 v[72:75], v[178:181], v[222:225], v[72:75]
	v_mfma_f32_16x16x32_bf16 v[64:67], v[186:189], v[222:225], v[64:67]
	s_barrier
	s_add_i32 s62, s62, s48
	s_mov_b32 m0, s62
	ds_read_b128 v[190:193], v173 offset:16384
	global_load_lds_dwordx4 v134, s[40:41]
	s_add_i32 m0, s62, 0x2000
	ds_read_b128 v[198:201], v244 offset:16384
	global_load_lds_dwordx4 v138, s[40:41]
	ds_read_b128 v[202:205], v173 offset:18432
	ds_read_b128 v[206:209], v244 offset:18432
	ds_read_b128 v[210:213], v173 offset:20480
	ds_read_b128 v[214:217], v244 offset:20480
	ds_read_b128 v[218:221], v173 offset:22528
	ds_read_b128 v[222:225], v244 offset:22528
	s_add_u32 s86, s40, 0x40000
	s_addc_u32 s87, s41, 0
	s_add_i32 s62, s63, s48
	s_waitcnt vmcnt(4)
	s_waitcnt lgkmcnt(0)
	s_barrier
	v_mfma_f32_16x16x32_bf16 v[60:63], v[128:131], v[190:193], v[60:63]
	v_mfma_f32_16x16x32_bf16 v[52:55], v[148:151], v[190:193], v[52:55]
	v_mfma_f32_16x16x32_bf16 v[44:47], v[128:131], v[202:205], v[44:47]
	s_mov_b32 m0, s62
	v_mfma_f32_16x16x32_bf16 v[36:39], v[148:151], v[202:205], v[36:39]
	v_mfma_f32_16x16x32_bf16 v[28:31], v[128:131], v[210:213], v[28:31]
	global_load_lds_dwordx4 v134, s[86:87]
	v_mfma_f32_16x16x32_bf16 v[20:23], v[148:151], v[210:213], v[20:23]
	v_mfma_f32_16x16x32_bf16 v[8:11], v[128:131], v[218:221], v[8:11]
	v_mfma_f32_16x16x32_bf16 v[4:7], v[148:151], v[218:221], v[4:7]
	v_mfma_f32_16x16x32_bf16 v[60:63], v[144:147], v[198:201], v[60:63]
	v_mfma_f32_16x16x32_bf16 v[52:55], v[152:155], v[198:201], v[52:55]
	v_mfma_f32_16x16x32_bf16 v[44:47], v[144:147], v[206:209], v[44:47]
	s_add_i32 m0, s62, 0x2000
	v_mfma_f32_16x16x32_bf16 v[36:39], v[152:155], v[206:209], v[36:39]
	v_mfma_f32_16x16x32_bf16 v[28:31], v[144:147], v[214:217], v[28:31]
	global_load_lds_dwordx4 v138, s[86:87]
	v_mfma_f32_16x16x32_bf16 v[20:23], v[152:155], v[214:217], v[20:23]
	v_mfma_f32_16x16x32_bf16 v[8:11], v[144:147], v[222:225], v[8:11]
	v_mfma_f32_16x16x32_bf16 v[4:7], v[152:155], v[222:225], v[4:7]
	v_mfma_f32_16x16x32_bf16 v[56:59], v[174:177], v[190:193], v[56:59]
	v_mfma_f32_16x16x32_bf16 v[48:51], v[182:185], v[190:193], v[48:51]
	v_mfma_f32_16x16x32_bf16 v[40:43], v[174:177], v[202:205], v[40:43]
	v_mfma_f32_16x16x32_bf16 v[32:35], v[182:185], v[202:205], v[32:35]
	v_mfma_f32_16x16x32_bf16 v[24:27], v[174:177], v[210:213], v[24:27]
	v_mfma_f32_16x16x32_bf16 v[16:19], v[182:185], v[210:213], v[16:19]
	v_mfma_f32_16x16x32_bf16 v[12:15], v[174:177], v[218:221], v[12:15]
	v_mfma_f32_16x16x32_bf16 v[0:3], v[182:185], v[218:221], v[0:3]
	v_mfma_f32_16x16x32_bf16 v[56:59], v[178:181], v[198:201], v[56:59]
	v_mfma_f32_16x16x32_bf16 v[48:51], v[186:189], v[198:201], v[48:51]
	v_mfma_f32_16x16x32_bf16 v[40:43], v[178:181], v[206:209], v[40:43]
	v_mfma_f32_16x16x32_bf16 v[32:35], v[186:189], v[206:209], v[32:35]
	v_mfma_f32_16x16x32_bf16 v[24:27], v[178:181], v[214:217], v[24:27]
	v_mfma_f32_16x16x32_bf16 v[16:19], v[186:189], v[214:217], v[16:19]
	v_mfma_f32_16x16x32_bf16 v[12:15], v[178:181], v[222:225], v[12:15]
	v_mfma_f32_16x16x32_bf16 v[0:3], v[186:189], v[222:225], v[0:3]
	s_barrier
	s_add_i32 s62, 0, 0x18000
	s_add_i32 s63, 0, 0x1c000
	s_mov_b32 m0, s51
	v_add_u32_e32 v152, s62, v172
	v_add_u32_e32 v158, s63, v172
	v_add_u32_e32 v245, s62, v243
	v_add_u32_e32 v246, s63, v243
	global_load_lds_dwordx4 v132, s[42:43]
	s_mov_b32 m0, s60
	ds_read_b128 v[128:131], v152
	global_load_lds_dwordx4 v136, s[42:43]
	ds_read_b128 v[144:147], v245
	ds_read_b128 v[148:151], v152 offset:2048
	ds_read_b128 v[152:155], v245 offset:2048
	ds_read_b128 v[174:177], v158
	ds_read_b128 v[178:181], v246
	ds_read_b128 v[182:185], v158 offset:2048
	ds_read_b128 v[186:189], v246 offset:2048
	ds_read_b128 v[190:193], v173 offset:32768
	ds_read_b128 v[198:201], v244 offset:32768
	ds_read_b128 v[202:205], v173 offset:34816
	ds_read_b128 v[206:209], v244 offset:34816
	ds_read_b128 v[210:213], v173 offset:36864
	ds_read_b128 v[214:217], v244 offset:36864
	ds_read_b128 v[218:221], v173 offset:38912
	ds_read_b128 v[222:225], v244 offset:38912
	s_add_u32 s42, s42, 0x40000
	s_addc_u32 s43, s43, 0
	s_waitcnt vmcnt(6)
	s_waitcnt lgkmcnt(0)
	s_barrier
	v_mfma_f32_16x16x32_bf16 v[124:127], v[128:131], v[190:193], v[124:127]
	v_mfma_f32_16x16x32_bf16 v[116:119], v[148:151], v[190:193], v[116:119]
	v_mfma_f32_16x16x32_bf16 v[108:111], v[128:131], v[202:205], v[108:111]
	s_mov_b32 m0, s61
	v_mfma_f32_16x16x32_bf16 v[100:103], v[148:151], v[202:205], v[100:103]
	v_mfma_f32_16x16x32_bf16 v[92:95], v[128:131], v[210:213], v[92:95]
	global_load_lds_dwordx4 v132, s[42:43]
	v_mfma_f32_16x16x32_bf16 v[84:87], v[148:151], v[210:213], v[84:87]
	v_mfma_f32_16x16x32_bf16 v[76:79], v[128:131], v[218:221], v[76:79]
	v_mfma_f32_16x16x32_bf16 v[68:71], v[148:151], v[218:221], v[68:71]
	v_mfma_f32_16x16x32_bf16 v[124:127], v[144:147], v[198:201], v[124:127]
	v_mfma_f32_16x16x32_bf16 v[116:119], v[152:155], v[198:201], v[116:119]
	v_mfma_f32_16x16x32_bf16 v[108:111], v[144:147], v[206:209], v[108:111]
	s_mov_b32 m0, s64
	v_mfma_f32_16x16x32_bf16 v[100:103], v[152:155], v[206:209], v[100:103]
	v_mfma_f32_16x16x32_bf16 v[92:95], v[144:147], v[214:217], v[92:95]
	global_load_lds_dwordx4 v136, s[42:43]
	v_mfma_f32_16x16x32_bf16 v[84:87], v[152:155], v[214:217], v[84:87]
	v_mfma_f32_16x16x32_bf16 v[76:79], v[144:147], v[222:225], v[76:79]
	v_mfma_f32_16x16x32_bf16 v[68:71], v[152:155], v[222:225], v[68:71]
	v_mfma_f32_16x16x32_bf16 v[120:123], v[174:177], v[190:193], v[120:123]
	v_mfma_f32_16x16x32_bf16 v[112:115], v[182:185], v[190:193], v[112:115]
	v_mfma_f32_16x16x32_bf16 v[104:107], v[174:177], v[202:205], v[104:107]
	v_mfma_f32_16x16x32_bf16 v[96:99], v[182:185], v[202:205], v[96:99]
	v_mfma_f32_16x16x32_bf16 v[88:91], v[174:177], v[210:213], v[88:91]
	v_mfma_f32_16x16x32_bf16 v[80:83], v[182:185], v[210:213], v[80:83]
	v_mfma_f32_16x16x32_bf16 v[72:75], v[174:177], v[218:221], v[72:75]
	v_mfma_f32_16x16x32_bf16 v[64:67], v[182:185], v[218:221], v[64:67]
	v_mfma_f32_16x16x32_bf16 v[120:123], v[178:181], v[198:201], v[120:123]
	v_mfma_f32_16x16x32_bf16 v[112:115], v[186:189], v[198:201], v[112:115]
	v_mfma_f32_16x16x32_bf16 v[104:107], v[178:181], v[206:209], v[104:107]
	v_mfma_f32_16x16x32_bf16 v[96:99], v[186:189], v[206:209], v[96:99]
	v_mfma_f32_16x16x32_bf16 v[88:91], v[178:181], v[214:217], v[88:91]
	v_mfma_f32_16x16x32_bf16 v[80:83], v[186:189], v[214:217], v[80:83]
	v_mfma_f32_16x16x32_bf16 v[72:75], v[178:181], v[222:225], v[72:75]
	v_mfma_f32_16x16x32_bf16 v[64:67], v[186:189], v[222:225], v[64:67]
	s_barrier
	s_add_i32 s42, s62, s48
	s_add_u32 s40, s40, 0x80
	s_addc_u32 s41, s41, 0
	s_mov_b32 m0, s42
	ds_read_b128 v[190:193], v173 offset:49152
	global_load_lds_dwordx4 v134, s[40:41]
	s_add_i32 m0, s42, 0x2000
	ds_read_b128 v[198:201], v244 offset:49152
	global_load_lds_dwordx4 v138, s[40:41]
	ds_read_b128 v[202:205], v173 offset:51200
	ds_read_b128 v[206:209], v244 offset:51200
	ds_read_b128 v[210:213], v173 offset:53248
	ds_read_b128 v[214:217], v244 offset:53248
	ds_read_b128 v[218:221], v173 offset:55296
	ds_read_b128 v[222:225], v244 offset:55296
	s_add_u32 s40, s40, 0x40000
	s_addc_u32 s41, s41, 0
	s_add_i32 s42, s63, s48
	s_waitcnt vmcnt(4)
	s_waitcnt lgkmcnt(0)
	s_barrier
	v_mfma_f32_16x16x32_bf16 v[60:63], v[128:131], v[190:193], v[60:63]
	v_mfma_f32_16x16x32_bf16 v[52:55], v[148:151], v[190:193], v[52:55]
	v_mfma_f32_16x16x32_bf16 v[44:47], v[128:131], v[202:205], v[44:47]
	s_mov_b32 m0, s42
	v_mfma_f32_16x16x32_bf16 v[36:39], v[148:151], v[202:205], v[36:39]
	v_mfma_f32_16x16x32_bf16 v[28:31], v[128:131], v[210:213], v[28:31]
	global_load_lds_dwordx4 v134, s[40:41]
	v_mfma_f32_16x16x32_bf16 v[20:23], v[148:151], v[210:213], v[20:23]
	v_mfma_f32_16x16x32_bf16 v[8:11], v[128:131], v[218:221], v[8:11]
	v_mfma_f32_16x16x32_bf16 v[4:7], v[148:151], v[218:221], v[4:7]
	v_mfma_f32_16x16x32_bf16 v[60:63], v[144:147], v[198:201], v[60:63]
	v_mfma_f32_16x16x32_bf16 v[52:55], v[152:155], v[198:201], v[52:55]
	v_mfma_f32_16x16x32_bf16 v[44:47], v[144:147], v[206:209], v[44:47]
	s_add_i32 m0, s42, 0x2000
	v_mfma_f32_16x16x32_bf16 v[36:39], v[152:155], v[206:209], v[36:39]
	v_mfma_f32_16x16x32_bf16 v[28:31], v[144:147], v[214:217], v[28:31]
	global_load_lds_dwordx4 v138, s[40:41]
	v_mfma_f32_16x16x32_bf16 v[20:23], v[152:155], v[214:217], v[20:23]
	v_mfma_f32_16x16x32_bf16 v[8:11], v[144:147], v[222:225], v[8:11]
	v_mfma_f32_16x16x32_bf16 v[4:7], v[152:155], v[222:225], v[4:7]
	v_mfma_f32_16x16x32_bf16 v[56:59], v[174:177], v[190:193], v[56:59]
	v_mfma_f32_16x16x32_bf16 v[48:51], v[182:185], v[190:193], v[48:51]
	v_mfma_f32_16x16x32_bf16 v[40:43], v[174:177], v[202:205], v[40:43]
	v_mfma_f32_16x16x32_bf16 v[32:35], v[182:185], v[202:205], v[32:35]
	v_mfma_f32_16x16x32_bf16 v[24:27], v[174:177], v[210:213], v[24:27]
	v_mfma_f32_16x16x32_bf16 v[16:19], v[182:185], v[210:213], v[16:19]
	v_mfma_f32_16x16x32_bf16 v[12:15], v[174:177], v[218:221], v[12:15]
	v_mfma_f32_16x16x32_bf16 v[0:3], v[182:185], v[218:221], v[0:3]
	v_mfma_f32_16x16x32_bf16 v[56:59], v[178:181], v[198:201], v[56:59]
	v_mfma_f32_16x16x32_bf16 v[48:51], v[186:189], v[198:201], v[48:51]
	v_mfma_f32_16x16x32_bf16 v[40:43], v[178:181], v[206:209], v[40:43]
	v_mfma_f32_16x16x32_bf16 v[32:35], v[186:189], v[206:209], v[32:35]
	v_mfma_f32_16x16x32_bf16 v[24:27], v[178:181], v[214:217], v[24:27]
	v_mfma_f32_16x16x32_bf16 v[16:19], v[186:189], v[214:217], v[16:19]
	v_mfma_f32_16x16x32_bf16 v[12:15], v[178:181], v[222:225], v[12:15]
	v_mfma_f32_16x16x32_bf16 v[0:3], v[186:189], v[222:225], v[0:3]
	s_barrier
	s_add_i32 s85, s85, 2
	s_add_u32 s34, s34, 0x100
	s_addc_u32 s35, s35, 0
	s_add_u32 s83, s83, 0x100
	s_addc_u32 s84, s84, 0
	s_cmp_gt_u32 s85, 13
	s_cbranch_scc0 .LBB0_629
	s_and_b64 vcc, exec, s[2:3]
	s_cbranch_vccz .LBB0_632
	s_barrier

.LBB0_703:
	s_setprio 0
	s_waitcnt vmcnt(0)
	s_movk_i32 s65, 0xff
	s_barrier
	s_cmp_lg_u32 s74, 0
	s_cbranch_scc1 .LBB0_800
